# static s_setprio 1 for waves 4-7 inside the attention key-tile loop (on the split-epilogue version)
# speedup vs baseline: 1.0040x; 1.0005x over previous
; #define LAS __attribute__((address_space(3)))
; #define AT_ADV() do { kg[0] += 64 * 1024; kg[1] += 64 * 1024; vg[0] += 64; vg[1] += 64; } while (0)
; __device__ __forceinline__ void attn_unit(unsigned char* ws, const float* sub_g, LAS unsigned char* lds, int h, int qb, float negM, float lam) {
;     const int tid = threadIdx.x, lane = tid & 63, r32 = lane & 31, hi = lane >> 5;
;     const int wid = __builtin_amdgcn_readfirstlane(tid >> 6), map = wid >> 2, wq = wid & 3;
;     const int qrow0 = qb * 128 + 32 * wq;
;     const bf16_t* Qp = (const bf16_t*)(ws + WS_Q); const bf16_t* Kp = (const bf16_t*)(ws + WS_K); const bf16_t* VTp = (const bf16_t*)(ws + WS_VT);
;     bf16x8 qf[4];
;     {
;         const bf16_t* qp = Qp + (size_t)(qrow0 + r32) * 1024 + (h * 2 + map) * 64 + 8 * hi;
; #pragma unroll
;         for (int d0 = 0; d0 < 4; ++d0) qf[d0] = *(const bf16x8*)(qp + 16 * d0);
;     }
;     const bf16_t* kg[2]; const bf16_t* vg[2];
; #pragma unroll
;     for (int i = 0; i < 2; ++i) {
;         const int g = 2 * wid + i;
;         const int kr = 4 * g + (lane >> 4), kc = (lane & 15) ^ (kr & 15);
;         kg[i] = Kp + (size_t)kr * 1024 + h * 128 + kc * 8;
;         const int vr = 8 * g + (lane >> 3), vc = (lane & 7) ^ ((vr >> 1) & 7);
;         vg[i] = VTp + (size_t)(h * 128 + vr) * NTOK + vc * 8;
;     }
;     const unsigned dmaoff = (unsigned)wid * 2048u;
;     ...
;     int kad[4], vad[4];
; #pragma unroll
;     for (int d0 = 0; d0 < 4; ++d0) kad[d0] = r32 * 256 + (((map * 8 + 2 * d0 + hi) ^ (r32 & 15)) << 4);
; #pragma unroll
;     for (int j = 0; j < 4; ++j) vad[j] = AT_KBYTES + r32 * 128 + (((2 * j + hi) ^ ((r32 >> 1) & 7)) << 4);
;     ...
;     f32x16 o[4];
; #pragma unroll
;     for (int b = 0; b < 4; ++b)
; #pragma unroll
;         for (int r = 0; r < 16; ++r) o[b][r] = 0.f;
;     f32x16 negm;
; #pragma unroll
;     for (int r = 0; r < 16; ++r) negm[r] = negM;
;     float l0 = 0.f, l1 = 0.f;
;     AT_DMA(0); AT_ADV();
;     asm volatile("s_waitcnt vmcnt(0)" ::: "memory");
;     __builtin_amdgcn_s_barrier();
;     AT_DMA(AT_BUF); AT_ADV();
;     f32x16 pa, pb;
;     {
;         f32x16 s0 = negm, s1 = negm;
; #pragma unroll
;         for (int d0 = 0; d0 < 4; ++d0) { s0 = __builtin_amdgcn_mfma_f32_32x32x16_bf16(KFR(0, d0, 0), qf[d0], s0, 0, 0, 0); s1 = __builtin_amdgcn_mfma_f32_32x32x16_bf16(KFR(0, d0, 1), qf[d0], s1, 0, 0, 0); }
.LBB0_830:
	v_readfirstlane_b32 s25, v220
	s_bfe_u32 s29, s25, 0x20006
	s_lshl_b32 s8, s20, 4
	s_and_b32 s8, s8, 0xffffff80
	s_lshl_b32 s21, s29, 5
	s_or_b32 s21, s21, s8
	s_lshr_b32 s28, s25, 8
	v_or_b32_e32 v16, s21, v153
	s_lshl_b32 s8, s20, 7
	v_ashrrev_i32_e32 v17, 31, v16
	s_and_b32 s24, s8, 0x380
	s_lshl_b32 s8, s28, 6
	v_lshlrev_b64 v[16:17], 11, v[16:17]
	s_add_i32 s8, s8, s24
	v_lshl_add_u64 v[16:17], s[4:5], 0, v[16:17]
	s_lshl_b32 s8, s8, 1
	v_lshl_add_u64 v[16:17], v[16:17], 0, s[8:9]
	v_lshlrev_b32_e32 v130, 4, v150
	s_mov_b64 s[34:35], 0x8000
	v_lshl_add_u64 v[16:17], v[16:17], 0, v[130:131]
	v_lshl_add_u64 v[18:19], v[16:17], 0, s[34:35]
	global_load_dwordx4 v[112:115], v[16:17], off
	global_load_dwordx4 v[116:119], v[16:17], off offset:64
	global_load_dwordx4 v[120:123], v[18:19], off
	global_load_dwordx4 v[124:127], v[18:19], off offset:64
	s_lshr_b32 s33, s25, 6
	s_lshr_b32 s8, s25, 5
	s_lshl_b32 s30, s24, 1
	s_add_u32 s30, s3, s30
	s_addc_u32 s31, s18, 0
	s_lshl_b32 s34, s33, 3
	s_bfe_u32 s98, s25, 0x10007
	s_lshl_b32 s98, s98, 3
	s_or_b32 s99, s98, 4
	v_or_b32_e32 v130, s34, v150
	v_bitop3_b32 v18, s98, v220, v150 bitop3:0x36
	v_lshlrev_b64 v[16:17], 11, v[130:131]
	v_lshlrev_b32_e32 v18, 4, v18
	v_lshl_add_u64 v[16:17], s[30:31], 0, v[16:17]
	v_and_b32_e32 v130, 0xf0, v18
	v_lshl_add_u64 v[56:57], v[16:17], 0, v[130:131]
	v_lshl_or_b32 v16, s33, 4, v151
	v_lshrrev_b32_e32 v17, 1, v151
	v_xor_b32_e32 v20, v17, v220
	v_add_u32_e32 v18, s24, v16
	v_mov_b64_e32 v[16:17], s[6:7]
	v_mad_u64_u32 v[18:19], s[34:35], v18, s19, v[16:17]
	v_lshlrev_b32_e32 v20, 4, v20
	s_or_b32 s8, s8, 1
	v_and_b32_e32 v130, 0x70, v20
	s_lshl_b32 s34, s8, 2
	v_lshl_add_u64 v[58:59], v[18:19], 0, v[130:131]
	v_or_b32_e32 v130, s34, v150
	v_bitop3_b32 v20, s99, v220, v150 bitop3:0x36
	v_lshlrev_b64 v[18:19], 11, v[130:131]
	v_lshlrev_b32_e32 v20, 4, v20
	v_lshl_add_u64 v[18:19], s[30:31], 0, v[18:19]
	v_and_b32_e32 v130, 0xf0, v20
	v_lshl_add_u64 v[60:61], v[18:19], 0, v[130:131]
	v_lshl_or_b32 v18, s8, 3, v151
	v_lshrrev_b32_e32 v19, 1, v18
	v_add_u32_e32 v18, s24, v18
	s_lshl_b32 s8, s33, 11
	v_mad_u64_u32 v[16:17], s[30:31], v18, s19, v[16:17]
	s_add_i32 s8, s8, 0
	v_xor_b32_e32 v19, v19, v220
	s_add_i32 s31, s8, 0x4000
	s_mov_b32 m0, s8
	v_lshlrev_b32_e32 v18, 4, v19
	global_load_lds_dwordx4 v[56:57], off
	s_mov_b32 m0, s31
	v_and_b32_e32 v130, 0x70, v18
	global_load_lds_dwordx4 v[58:59], off
	s_add_i32 m0, s8, 0x400
	v_lshl_add_u64 v[62:63], v[16:17], 0, v[130:131]
	global_load_lds_dwordx4 v[60:61], off
	s_add_i32 m0, s8, 0x4400
	v_lshl_add_u64 v[16:17], v[56:57], 0, s[10:11]
	global_load_lds_dwordx4 v[62:63], off
	s_add_i32 m0, s8, 0x8000
	s_add_i32 s31, s8, 0xc000
	v_lshl_add_u64 v[20:21], v[58:59], 0, s[12:13]
	global_load_lds_dwordx4 v[16:17], off
	s_mov_b32 m0, s31
	v_lshl_add_u64 v[18:19], v[60:61], 0, s[10:11]
	global_load_lds_dwordx4 v[20:21], off
	s_add_i32 m0, s8, 0x8400
	v_lshl_add_u64 v[22:23], v[62:63], 0, s[12:13]
	global_load_lds_dwordx4 v[18:19], off
	s_add_i32 m0, s8, 0xc400
	s_lshl_b32 s30, s28, 3
	global_load_lds_dwordx4 v[22:23], off
	v_lshl_add_u64 v[140:141], v[56:57], 0, s[14:15]
	v_lshl_add_u64 v[142:143], v[60:61], 0, s[14:15]
	v_lshl_add_u64 v[144:145], v[58:59], 0, s[16:17]
	v_lshl_add_u64 v[146:147], v[62:63], 0, s[16:17]
	s_add_i32 m0, s8, 0x10000
	s_nop 0
	global_load_lds_dwordx4 v[140:141], off
	s_add_i32 m0, s8, 0x14000
	s_nop 0
	global_load_lds_dwordx4 v[144:145], off
	s_add_i32 m0, s8, 0x10400
	s_nop 0
	global_load_lds_dwordx4 v[142:143], off
	s_add_i32 m0, s8, 0x14400
	s_nop 0
	global_load_lds_dwordx4 v[146:147], off
	s_waitcnt vmcnt(8)
	s_barrier
	v_lshl_add_u64 v[140:141], v[140:141], 0, s[10:11]
	v_lshl_add_u64 v[142:143], v[142:143], 0, s[10:11]
	v_lshl_add_u64 v[144:145], v[144:145], 0, s[12:13]
	v_lshl_add_u64 v[146:147], v[146:147], 0, s[12:13]
	s_mov_b32 s98, s3
	s_mov_b32 s99, s18
	s_mov_b64 s[100:101], s[6:7]
	v_subrev_u32_e32 v140, s3, v140
	v_subrev_u32_e32 v142, s3, v142
	v_subrev_u32_e32 v144, s6, v144
	v_subrev_u32_e32 v146, s6, v146
	s_mov_b32 s33, 1
	v_bitop3_b32 v24, s30, v153, v150 bitop3:0x36
	v_lshlrev_b32_e32 v25, 8, v153
	v_and_b32_e32 v26, 0x700, v25
	v_and_b32_e32 v25, 0x800, v25
	v_lshl_or_b32 v26, v25, 1, v26
	v_lshl_add_u32 v198, v24, 4, v26
	v_xor_b32_e32 v200, 64, v198
	v_lshrrev_b32_e32 v24, 1, v153
	v_xor_b32_e32 v24, v24, v150
	v_lshlrev_b32_e32 v25, 7, v153
	v_lshl_add_u32 v201, v24, 4, v25
	v_xor_b32_e32 v202, 64, v201
	v_add_u32_e32 v247, 0x10000, v198
	v_add_u32_e32 v248, 0x10000, v200
	v_add_u32_e32 v249, 0x10000, v201
	v_add_u32_e32 v250, 0x10000, v202
	ds_read_b128 v[16:19], v198
	ds_read_b128 v[20:23], v200
	ds_read_b128 v[24:27], v198 offset:2048
	ds_read_b128 v[28:31], v200 offset:2048
	ds_read_b128 v[32:35], v198 offset:8192
	ds_read_b128 v[36:39], v200 offset:8192
	ds_read_b128 v[40:43], v198 offset:10240
	ds_read_b128 v[44:47], v200 offset:10240
	s_waitcnt lgkmcnt(7)
	v_mfma_f32_16x16x32_bf16 v[80:83], v[16:19], v[112:115], v[0:3]
	v_mfma_f32_16x16x32_bf16 v[84:87], v[16:19], v[120:123], v[0:3]
	s_waitcnt lgkmcnt(6)
	v_mfma_f32_16x16x32_bf16 v[80:83], v[20:23], v[116:119], v[80:83]
	v_mfma_f32_16x16x32_bf16 v[84:87], v[20:23], v[124:127], v[84:87]
	s_waitcnt lgkmcnt(5)
	v_mfma_f32_16x16x32_bf16 v[88:91], v[24:27], v[112:115], v[0:3]
	v_mfma_f32_16x16x32_bf16 v[92:95], v[24:27], v[120:123], v[0:3]
	s_waitcnt lgkmcnt(4)
	v_mfma_f32_16x16x32_bf16 v[88:91], v[28:31], v[116:119], v[88:91]
	v_mfma_f32_16x16x32_bf16 v[92:95], v[28:31], v[124:127], v[92:95]
	s_waitcnt lgkmcnt(3)
	v_mfma_f32_16x16x32_bf16 v[96:99], v[32:35], v[112:115], v[0:3]
	v_mfma_f32_16x16x32_bf16 v[100:103], v[32:35], v[120:123], v[0:3]
	s_waitcnt lgkmcnt(2)
; #define SB() __builtin_amdgcn_sched_barrier(0)
; __device__ __forceinline__ void attn_unit(unsigned char* ws, const float* sub_g, LAS unsigned char* lds, int h, int qb, float negM, float lam) {
;     ...
;     {
;         f32x16 s0 = negm, s1 = negm;
; #pragma unroll
;         for (int d0 = 0; d0 < 4; ++d0) { s0 = __builtin_amdgcn_mfma_f32_32x32x16_bf16(KFR(0, d0, 0), qf[d0], s0, 0, 0, 0); s1 = __builtin_amdgcn_mfma_f32_32x32x16_bf16(KFR(0, d0, 1), qf[d0], s1, 0, 0, 0); }
; #pragma unroll
;         for (int r = 0; r < 16; ++r) { pa[r] = __builtin_amdgcn_exp2f(s0[r]); pb[r] = __builtin_amdgcn_exp2f(s1[r]); }
;     }
;     asm volatile("s_waitcnt vmcnt(0) lgkmcnt(0)" ::: "memory");
;     __builtin_amdgcn_s_barrier();
;     int bV = 0, bK = AT_BUF, bW = 2 * AT_BUF;
;     u32x4 pw[4];
;     for (int t = 1; t < AT_NT; ++t) {
;         AT_DMA(bW);
;         if (t + 2 < AT_NT) AT_ADV();
;         SB();
;     ...
;         f32x16 s0, s1;
;         bf16x8 F0 = FLOAD(0), F1 = FLOAD(1), F2;
;         SB();
;         F2 = FLOAD(2); s0 = __builtin_amdgcn_mfma_f32_32x32x16_bf16(F0, qf[0], negm, 0, 0, 0); ADD4(pa, 0); pw[0][0] = cvtpk(pa[0], pa[1]); SB();
;         F0 = FLOAD(3); s1 = __builtin_amdgcn_mfma_f32_32x32x16_bf16(F1, qf[0], negm, 0, 0, 0); ADD4(pa, 4); pw[0][1] = cvtpk(pa[2], pa[3]); SB();
;         F1 = FLOAD(4); s0 = __builtin_amdgcn_mfma_f32_32x32x16_bf16(F2, qf[1], s0, 0, 0, 0); ADD4(pa, 8); pw[0][2] = cvtpk(pa[4], pa[5]); SB();
;         F2 = FLOAD(5); s1 = __builtin_amdgcn_mfma_f32_32x32x16_bf16(F0, qf[1], s1, 0, 0, 0); ADD4(pa, 12); pw[0][3] = cvtpk(pa[6], pa[7]); SB();
;         F0 = FLOAD(6); s0 = __builtin_amdgcn_mfma_f32_32x32x16_bf16(F1, qf[2], s0, 0, 0, 0); ADD4(pb, 0); pw[1][0] = cvtpk(pa[8], pa[9]); SB();
;         F1 = FLOAD(7); s1 = __builtin_amdgcn_mfma_f32_32x32x16_bf16(F2, qf[2], s1, 0, 0, 0); ADD4(pb, 4); pw[1][1] = cvtpk(pa[10], pa[11]); SB();
;         F2 = FLOAD(8); s0 = __builtin_amdgcn_mfma_f32_32x32x16_bf16(F0, qf[3], s0, 0, 0, 0); ADD4(pb, 8); pw[1][2] = cvtpk(pa[12], pa[13]); SB();
;         F0 = FLOAD(9); s1 = __builtin_amdgcn_mfma_f32_32x32x16_bf16(F1, qf[3], s1, 0, 0, 0); ADD4(pb, 12); pw[1][3] = cvtpk(pa[14], pa[15]); SB();
;         F1 = FLOAD(10); o[0] = __builtin_amdgcn_mfma_f32_32x32x16_bf16(F2, __builtin_bit_cast(bf16x8, pw[0]), o[0], 0, 0, 0); pw[2][0] = cvtpk(pb[0], pb[1]); EXP2(s0, pa, 0); SB();
	v_mfma_f32_16x16x32_bf16 v[96:99], v[36:39], v[116:119], v[96:99]
	v_mfma_f32_16x16x32_bf16 v[100:103], v[36:39], v[124:127], v[100:103]
	s_waitcnt lgkmcnt(1)
	v_mfma_f32_16x16x32_bf16 v[104:107], v[40:43], v[112:115], v[0:3]
	v_mfma_f32_16x16x32_bf16 v[108:111], v[40:43], v[120:123], v[0:3]
	s_waitcnt lgkmcnt(0)
	v_mfma_f32_16x16x32_bf16 v[104:107], v[44:47], v[116:119], v[104:107]
	v_mfma_f32_16x16x32_bf16 v[108:111], v[44:47], v[124:127], v[108:111]
	s_nop 7
	s_nop 1
	v_exp_f32_e32 v183, v80
	v_exp_f32_e32 v184, v81
	v_exp_f32_e32 v185, v82
	v_exp_f32_e32 v186, v83
	v_exp_f32_e32 v187, v84
	v_exp_f32_e32 v188, v85
	v_exp_f32_e32 v189, v86
	v_exp_f32_e32 v190, v87
	v_exp_f32_e32 v191, v88
	v_exp_f32_e32 v192, v89
	v_exp_f32_e32 v193, v90
	v_exp_f32_e32 v194, v91
	v_exp_f32_e32 v195, v92
	v_exp_f32_e32 v196, v93
	v_exp_f32_e32 v197, v94
	v_exp_f32_e32 v199, v95
	v_exp_f32_e32 v203, v96
	v_exp_f32_e32 v204, v97
	v_exp_f32_e32 v205, v98
	v_exp_f32_e32 v206, v99
	v_exp_f32_e32 v207, v100
	v_exp_f32_e32 v208, v101
	v_exp_f32_e32 v209, v102
	v_exp_f32_e32 v210, v103
	v_exp_f32_e32 v211, v104
	v_exp_f32_e32 v213, v105
	v_exp_f32_e32 v214, v106
	v_exp_f32_e32 v215, v107
	v_exp_f32_e32 v216, v108
	v_exp_f32_e32 v217, v109
	v_exp_f32_e32 v218, v110
	v_exp_f32_e32 v219, v111
	v_mov_b32_e32 v16, 0
	v_mov_b32_e32 v17, 0
	v_mov_b32_e32 v18, 0
	v_mov_b32_e32 v19, 0
	v_mov_b32_e32 v20, 0
	v_mov_b32_e32 v21, 0
	v_mov_b32_e32 v22, 0
	v_mov_b32_e32 v23, 0
	v_mov_b32_e32 v24, 0
	v_mov_b32_e32 v25, 0
	v_mov_b32_e32 v26, 0
	v_mov_b32_e32 v27, 0
	v_mov_b32_e32 v28, 0
	v_mov_b32_e32 v29, 0
	v_mov_b32_e32 v30, 0
	v_mov_b32_e32 v31, 0
	v_mov_b32_e32 v32, 0
	v_mov_b32_e32 v33, 0
	v_mov_b32_e32 v34, 0
	v_mov_b32_e32 v35, 0
	v_mov_b32_e32 v36, 0
	v_mov_b32_e32 v37, 0
	v_mov_b32_e32 v38, 0
	v_mov_b32_e32 v39, 0
	v_mov_b32_e32 v40, 0
	v_mov_b32_e32 v41, 0
	v_mov_b32_e32 v42, 0
	v_mov_b32_e32 v43, 0
	v_mov_b32_e32 v44, 0
	v_mov_b32_e32 v45, 0
	v_mov_b32_e32 v46, 0
	v_mov_b32_e32 v47, 0
	v_mov_b32_e32 v48, 0
	v_mov_b32_e32 v49, 0
	v_mov_b32_e32 v50, 0
	v_mov_b32_e32 v51, 0
	v_mov_b32_e32 v52, 0
	v_mov_b32_e32 v53, 0
	v_mov_b32_e32 v54, 0
	v_mov_b32_e32 v55, 0
	v_mov_b32_e32 v56, 0
	v_mov_b32_e32 v57, 0
	v_mov_b32_e32 v58, 0
	v_mov_b32_e32 v59, 0
	v_mov_b32_e32 v60, 0
	v_mov_b32_e32 v61, 0
	v_mov_b32_e32 v62, 0
	v_mov_b32_e32 v63, 0
	v_mov_b32_e32 v64, 0
	v_mov_b32_e32 v65, 0
	v_mov_b32_e32 v66, 0
	v_mov_b32_e32 v67, 0
	v_mov_b32_e32 v68, 0
	v_mov_b32_e32 v69, 0
	v_mov_b32_e32 v70, 0
	v_mov_b32_e32 v71, 0
	v_mov_b32_e32 v72, 0
	v_mov_b32_e32 v73, 0
	v_mov_b32_e32 v74, 0
	v_mov_b32_e32 v75, 0
	v_mov_b32_e32 v76, 0
	v_mov_b32_e32 v77, 0
	v_mov_b32_e32 v78, 0
	v_mov_b32_e32 v79, 0
	v_mov_b32_e32 v222, 0
	v_mov_b32_e32 v223, 0
	s_waitcnt vmcnt(4)
	s_barrier
	ds_read_b128 v[4:7], v198 offset:32768
	ds_read_b128 v[8:11], v200 offset:32768
	ds_read_b128 v[12:15], v198 offset:34816
	s_cmpk_lt_u32 s25, 0x100
	s_cbranch_scc1 .Lprio_skip
	s_setprio 1
.Lprio_skip:
	s_branch .Lattn_c1
.Lattn_c1:
	s_waitcnt lgkmcnt(1)
	v_mfma_f32_16x16x32_bf16 v[80:83], v[4:7], v[112:115], v[0:3]
	ds_read_b128 v[224:227], v200 offset:34816
	v_add_f32_e32 v222, v222, v183
	v_add_f32_e32 v223, v223, v187
	v_cvt_pk_bf16_f32 v232, v183, v184
	v_mfma_f32_16x16x32_bf16 v[84:87], v[4:7], v[120:123], v[0:3]
	v_add_f32_e32 v222, v222, v184
	v_add_f32_e32 v223, v223, v188
	v_mfma_f32_16x16x32_bf16 v[80:83], v[8:11], v[116:119], v[80:83]
	ds_read_b128 v[4:7], v198 offset:40960
	v_add_f32_e32 v222, v222, v185
	v_add_f32_e32 v223, v223, v189
	v_cvt_pk_bf16_f32 v233, v185, v186
	v_mfma_f32_16x16x32_bf16 v[84:87], v[8:11], v[124:127], v[84:87]
	v_add_f32_e32 v222, v222, v186
	v_add_f32_e32 v223, v223, v190
	s_waitcnt lgkmcnt(1)
	v_mfma_f32_16x16x32_bf16 v[88:91], v[12:15], v[112:115], v[0:3]
	ds_read_b128 v[8:11], v200 offset:40960
	v_add_f32_e32 v222, v222, v191
	v_add_f32_e32 v223, v223, v195
	v_cvt_pk_bf16_f32 v234, v191, v192
	v_mfma_f32_16x16x32_bf16 v[92:95], v[12:15], v[120:123], v[0:3]
	v_add_f32_e32 v222, v222, v192
	v_add_f32_e32 v223, v223, v196
	v_mfma_f32_16x16x32_bf16 v[88:91], v[224:227], v[116:119], v[88:91]
	ds_read_b128 v[12:15], v198 offset:43008
	v_add_f32_e32 v222, v222, v193
	v_add_f32_e32 v223, v223, v197
	v_cvt_pk_bf16_f32 v235, v193, v194
	v_mfma_f32_16x16x32_bf16 v[92:95], v[224:227], v[124:127], v[92:95]
	v_add_f32_e32 v222, v222, v194
	v_add_f32_e32 v223, v223, v199
	s_waitcnt lgkmcnt(1)
	v_mfma_f32_16x16x32_bf16 v[96:99], v[4:7], v[112:115], v[0:3]
	ds_read_b128 v[224:227], v200 offset:43008
	v_add_f32_e32 v222, v222, v203
	v_add_f32_e32 v223, v223, v207
	v_cvt_pk_bf16_f32 v236, v187, v188
	v_mfma_f32_16x16x32_bf16 v[100:103], v[4:7], v[120:123], v[0:3]
	v_add_f32_e32 v222, v222, v204
	v_add_f32_e32 v223, v223, v208
	v_mfma_f32_16x16x32_bf16 v[96:99], v[8:11], v[116:119], v[96:99]
	ds_read_b128 v[4:7], v201 offset:16384
	v_add_f32_e32 v222, v222, v205
	v_add_f32_e32 v223, v223, v209
	v_cvt_pk_bf16_f32 v237, v189, v190
	v_mfma_f32_16x16x32_bf16 v[100:103], v[8:11], v[124:127], v[100:103]
	v_add_f32_e32 v222, v222, v206
	v_add_f32_e32 v223, v223, v210
	s_waitcnt lgkmcnt(1)
	v_mfma_f32_16x16x32_bf16 v[104:107], v[12:15], v[112:115], v[0:3]
	ds_read_b128 v[8:11], v201 offset:18432
	v_add_f32_e32 v222, v222, v211
	v_add_f32_e32 v223, v223, v216
	v_cvt_pk_bf16_f32 v238, v195, v196
	v_mfma_f32_16x16x32_bf16 v[108:111], v[12:15], v[120:123], v[0:3]
	v_add_f32_e32 v222, v222, v213
	v_add_f32_e32 v223, v223, v217
	v_mfma_f32_16x16x32_bf16 v[104:107], v[224:227], v[116:119], v[104:107]
	ds_read_b128 v[12:15], v201 offset:20480
	v_add_f32_e32 v222, v222, v214
	v_add_f32_e32 v223, v223, v218
	v_cvt_pk_bf16_f32 v239, v197, v199
	v_mfma_f32_16x16x32_bf16 v[108:111], v[224:227], v[124:127], v[108:111]
	v_add_f32_e32 v222, v222, v215
	v_add_f32_e32 v223, v223, v219
	s_waitcnt vmcnt(0)
	s_barrier
; #define AT_ADV() do { kg[0] += 64 * 1024; kg[1] += 64 * 1024; vg[0] += 64; vg[1] += 64; } while (0)
; #define SB() __builtin_amdgcn_sched_barrier(0)
; __device__ __forceinline__ void attn_unit(unsigned char* ws, const float* sub_g, LAS unsigned char* lds, int h, int qb, float negM, float lam) {
;     ...
;         AT_DMA(bW);
;         if (t + 2 < AT_NT) AT_ADV();
;         SB();
;     ...
;         f32x16 s0, s1;
;         bf16x8 F0 = FLOAD(0), F1 = FLOAD(1), F2;
;         SB();
;         F2 = FLOAD(2); s0 = __builtin_amdgcn_mfma_f32_32x32x16_bf16(F0, qf[0], negm, 0, 0, 0); ADD4(pa, 0); pw[0][0] = cvtpk(pa[0], pa[1]); SB();
;         F0 = FLOAD(3); s1 = __builtin_amdgcn_mfma_f32_32x32x16_bf16(F1, qf[0], negm, 0, 0, 0); ADD4(pa, 4); pw[0][1] = cvtpk(pa[2], pa[3]); SB();
;         F1 = FLOAD(4); s0 = __builtin_amdgcn_mfma_f32_32x32x16_bf16(F2, qf[1], s0, 0, 0, 0); ADD4(pa, 8); pw[0][2] = cvtpk(pa[4], pa[5]); SB();
;         F2 = FLOAD(5); s1 = __builtin_amdgcn_mfma_f32_32x32x16_bf16(F0, qf[1], s1, 0, 0, 0); ADD4(pa, 12); pw[0][3] = cvtpk(pa[6], pa[7]); SB();
;         F0 = FLOAD(6); s0 = __builtin_amdgcn_mfma_f32_32x32x16_bf16(F1, qf[2], s0, 0, 0, 0); ADD4(pb, 0); pw[1][0] = cvtpk(pa[8], pa[9]); SB();
;         F1 = FLOAD(7); s1 = __builtin_amdgcn_mfma_f32_32x32x16_bf16(F2, qf[2], s1, 0, 0, 0); ADD4(pb, 4); pw[1][1] = cvtpk(pa[10], pa[11]); SB();
;         F2 = FLOAD(8); s0 = __builtin_amdgcn_mfma_f32_32x32x16_bf16(F0, qf[3], s0, 0, 0, 0); ADD4(pb, 8); pw[1][2] = cvtpk(pa[12], pa[13]); SB();
;         F0 = FLOAD(9); s1 = __builtin_amdgcn_mfma_f32_32x32x16_bf16(F1, qf[3], s1, 0, 0, 0); ADD4(pb, 12); pw[1][3] = cvtpk(pa[14], pa[15]); SB();
;         F1 = FLOAD(10); o[0] = __builtin_amdgcn_mfma_f32_32x32x16_bf16(F2, __builtin_bit_cast(bf16x8, pw[0]), o[0], 0, 0, 0); pw[2][0] = cvtpk(pb[0], pb[1]); EXP2(s0, pa, 0); SB();
;         F2 = FLOAD(11); o[1] = __builtin_amdgcn_mfma_f32_32x32x16_bf16(F0, __builtin_bit_cast(bf16x8, pw[0]), o[1], 0, 0, 0); pw[2][1] = cvtpk(pb[2], pb[3]); EXP2(s0, pa, 2); SB();
;         F0 = FLOAD(12); o[2] = __builtin_amdgcn_mfma_f32_32x32x16_bf16(F1, __builtin_bit_cast(bf16x8, pw[0]), o[2], 0, 0, 0); pw[2][2] = cvtpk(pb[4], pb[5]); EXP2(s0, pa, 4); SB();
;         F1 = FLOAD(13); o[3] = __builtin_amdgcn_mfma_f32_32x32x16_bf16(F2, __builtin_bit_cast(bf16x8, pw[0]), o[3], 0, 0, 0); pw[2][3] = cvtpk(pb[6], pb[7]); EXP2(s0, pa, 6); SB();
	s_waitcnt lgkmcnt(1)
	v_mfma_f32_16x16x32_bf16 v[64:67], v[4:7], v[232:235], v[64:67]
	s_add_i32 m0, s8, 0x18000
	ds_read_b128 v[224:227], v201 offset:22528
	global_load_lds_dwordx4 v140, s[98:99]
	v_exp_f32_e32 v183, v80
	v_cvt_pk_bf16_f32 v228, v203, v204
	v_mfma_f32_16x16x32_bf16 v[68:71], v[4:7], v[236:239], v[68:71]
	v_exp_f32_e32 v184, v81
	v_mfma_f32_16x16x32_bf16 v[72:75], v[8:11], v[232:235], v[72:75]
	s_add_i32 m0, m0, 0x4000
	ds_read_b128 v[4:7], v201 offset:24576
	global_load_lds_dwordx4 v144, s[100:101]
	v_exp_f32_e32 v185, v82
	v_cvt_pk_bf16_f32 v229, v205, v206
	v_mfma_f32_16x16x32_bf16 v[76:79], v[8:11], v[236:239], v[76:79]
	v_exp_f32_e32 v186, v83
	s_waitcnt lgkmcnt(1)
	v_mfma_f32_16x16x32_bf16 v[48:51], v[12:15], v[232:235], v[48:51]
	s_add_i32 m0, m0, 0xffffc400
	ds_read_b128 v[8:11], v201 offset:26624
	global_load_lds_dwordx4 v142, s[98:99]
	v_exp_f32_e32 v187, v84
	v_cvt_pk_bf16_f32 v230, v211, v213
	v_mfma_f32_16x16x32_bf16 v[52:55], v[12:15], v[236:239], v[52:55]
	v_exp_f32_e32 v188, v85
	v_mfma_f32_16x16x32_bf16 v[56:59], v[224:227], v[232:235], v[56:59]
	s_add_i32 m0, m0, 0x4000
	ds_read_b128 v[12:15], v201 offset:28672
	global_load_lds_dwordx4 v146, s[100:101]
	s_add_u32 s98, s98, 0x20000
	s_addc_u32 s99, s99, 0
	s_add_u32 s100, s100, 0x80
	s_addc_u32 s101, s101, 0
	v_exp_f32_e32 v189, v86
	v_cvt_pk_bf16_f32 v231, v214, v215
	v_mfma_f32_16x16x32_bf16 v[60:63], v[224:227], v[236:239], v[60:63]
	v_exp_f32_e32 v190, v87
	s_waitcnt lgkmcnt(1)
	v_mfma_f32_16x16x32_bf16 v[32:35], v[4:7], v[232:235], v[32:35]
	ds_read_b128 v[224:227], v201 offset:30720
	v_exp_f32_e32 v191, v88
	v_cvt_pk_bf16_f32 v240, v207, v208
	v_mfma_f32_16x16x32_bf16 v[36:39], v[4:7], v[236:239], v[36:39]
	v_exp_f32_e32 v192, v89
	v_mfma_f32_16x16x32_bf16 v[40:43], v[8:11], v[232:235], v[40:43]
	ds_read_b128 v[4:7], v202 offset:16384
	v_exp_f32_e32 v193, v90
	v_cvt_pk_bf16_f32 v241, v209, v210
	v_mfma_f32_16x16x32_bf16 v[44:47], v[8:11], v[236:239], v[44:47]
	v_exp_f32_e32 v194, v91
	s_waitcnt lgkmcnt(1)
	v_mfma_f32_16x16x32_bf16 v[16:19], v[12:15], v[232:235], v[16:19]
	ds_read_b128 v[8:11], v202 offset:18432
	v_exp_f32_e32 v195, v92
	v_cvt_pk_bf16_f32 v242, v216, v217
	v_mfma_f32_16x16x32_bf16 v[20:23], v[12:15], v[236:239], v[20:23]
	v_exp_f32_e32 v196, v93
	v_mfma_f32_16x16x32_bf16 v[24:27], v[224:227], v[232:235], v[24:27]
	ds_read_b128 v[12:15], v202 offset:20480
	v_exp_f32_e32 v197, v94
	v_cvt_pk_bf16_f32 v243, v218, v219
	v_mfma_f32_16x16x32_bf16 v[28:31], v[224:227], v[236:239], v[28:31]
	v_exp_f32_e32 v199, v95
	s_waitcnt lgkmcnt(1)
	v_mfma_f32_16x16x32_bf16 v[64:67], v[4:7], v[228:231], v[64:67]
	ds_read_b128 v[224:227], v202 offset:22528
	v_exp_f32_e32 v203, v96
	v_mfma_f32_16x16x32_bf16 v[68:71], v[4:7], v[240:243], v[68:71]
	v_exp_f32_e32 v204, v97
	v_mfma_f32_16x16x32_bf16 v[72:75], v[8:11], v[228:231], v[72:75]
	ds_read_b128 v[4:7], v202 offset:24576
	v_exp_f32_e32 v205, v98
	v_mfma_f32_16x16x32_bf16 v[76:79], v[8:11], v[240:243], v[76:79]
	v_exp_f32_e32 v206, v99
	s_waitcnt lgkmcnt(1)
	v_mfma_f32_16x16x32_bf16 v[48:51], v[12:15], v[228:231], v[48:51]
	ds_read_b128 v[8:11], v202 offset:26624
	v_exp_f32_e32 v207, v100
	v_mfma_f32_16x16x32_bf16 v[52:55], v[12:15], v[240:243], v[52:55]
	v_exp_f32_e32 v208, v101
	v_mfma_f32_16x16x32_bf16 v[56:59], v[224:227], v[228:231], v[56:59]
	ds_read_b128 v[12:15], v202 offset:28672
	v_exp_f32_e32 v209, v102
	v_mfma_f32_16x16x32_bf16 v[60:63], v[224:227], v[240:243], v[60:63]
	v_exp_f32_e32 v210, v103
	s_waitcnt lgkmcnt(1)
	v_mfma_f32_16x16x32_bf16 v[32:35], v[4:7], v[228:231], v[32:35]
	ds_read_b128 v[224:227], v202 offset:30720
	v_exp_f32_e32 v211, v104
	v_mfma_f32_16x16x32_bf16 v[36:39], v[4:7], v[240:243], v[36:39]
	v_exp_f32_e32 v213, v105
	v_mfma_f32_16x16x32_bf16 v[40:43], v[8:11], v[228:231], v[40:43]
	ds_read_b128 v[4:7], v247
	v_exp_f32_e32 v214, v106
	v_mfma_f32_16x16x32_bf16 v[44:47], v[8:11], v[240:243], v[44:47]
	v_exp_f32_e32 v215, v107
	s_waitcnt lgkmcnt(1)
	v_mfma_f32_16x16x32_bf16 v[16:19], v[12:15], v[228:231], v[16:19]
	ds_read_b128 v[8:11], v248
	v_exp_f32_e32 v216, v108
	v_mfma_f32_16x16x32_bf16 v[20:23], v[12:15], v[240:243], v[20:23]
	v_exp_f32_e32 v217, v109
	v_mfma_f32_16x16x32_bf16 v[24:27], v[224:227], v[228:231], v[24:27]
	ds_read_b128 v[12:15], v247 offset:2048
	v_exp_f32_e32 v218, v110
	v_mfma_f32_16x16x32_bf16 v[28:31], v[224:227], v[240:243], v[28:31]
	v_exp_f32_e32 v219, v111
	s_add_i32 s33, s33, 1

; __device__ __forceinline__ unsigned cvtpk(float lo, float hi) { f32x2 v = {lo, hi}; bf16x2_t b = __builtin_convertvector(v, bf16x2_t); return __builtin_bit_cast(unsigned, b); }
; __device__ __forceinline__ void attn_unit(unsigned char* ws, const float* sub_g, LAS unsigned char* lds, int h, int qb, float negM, float lam) {
;     ...
;     {
;         float a0 = 0.f, a1 = 0.f;
; #pragma unroll
;         for (int r = 0; r < 16; ++r) { a0 += pa[r]; a1 += pb[r]; }
;         l0 += a0; l1 += a1;
;         pw[0] = (u32x4){cvtpk(pa[0], pa[1]), cvtpk(pa[2], pa[3]), cvtpk(pa[4], pa[5]), cvtpk(pa[6], pa[7])};
;         pw[1] = (u32x4){cvtpk(pa[8], pa[9]), cvtpk(pa[10], pa[11]), cvtpk(pa[12], pa[13]), cvtpk(pa[14], pa[15])};
;         pw[2] = (u32x4){cvtpk(pb[0], pb[1]), cvtpk(pb[2], pb[3]), cvtpk(pb[4], pb[5]), cvtpk(pb[6], pb[7])};
;         pw[3] = (u32x4){cvtpk(pb[8], pb[9]), cvtpk(pb[10], pb[11]), cvtpk(pb[12], pb[13]), cvtpk(pb[14], pb[15])};
; #pragma unroll
;         for (int j = 0; j < 4; ++j)
; #pragma unroll
;             for (int b = 0; b < 4; ++b) o[b] = __builtin_amdgcn_mfma_f32_32x32x16_bf16(VFR(bV, j, b), __builtin_bit_cast(bf16x8, pw[j]), o[b], 0, 0, 0);
;     }
.Lattn_exit:
	s_setprio 0
	s_waitcnt lgkmcnt(0)
	ds_read_b128 v[80:83], v249 offset:49152
	ds_read_b128 v[84:87], v249 offset:51200
	ds_read_b128 v[88:91], v249 offset:53248
	ds_read_b128 v[92:95], v249 offset:55296
	ds_read_b128 v[96:99], v249 offset:57344
	ds_read_b128 v[100:103], v249 offset:59392
	ds_read_b128 v[104:107], v249 offset:61440
	ds_read_b128 v[108:111], v249 offset:63488
	v_add_f32_e32 v222, v222, v183
	v_add_f32_e32 v223, v223, v187
	v_add_f32_e32 v222, v222, v184
	v_add_f32_e32 v223, v223, v188
	v_add_f32_e32 v222, v222, v185
	v_add_f32_e32 v223, v223, v189
	v_add_f32_e32 v222, v222, v186
	v_add_f32_e32 v223, v223, v190
	v_add_f32_e32 v222, v222, v191
	v_add_f32_e32 v223, v223, v195
	v_add_f32_e32 v222, v222, v192
	v_add_f32_e32 v223, v223, v196
	v_add_f32_e32 v222, v222, v193
	v_add_f32_e32 v223, v223, v197
	v_add_f32_e32 v222, v222, v194
	v_add_f32_e32 v223, v223, v199
	v_add_f32_e32 v222, v222, v203
	v_add_f32_e32 v223, v223, v207
	v_add_f32_e32 v222, v222, v204
	v_add_f32_e32 v223, v223, v208
	v_add_f32_e32 v222, v222, v205
	v_add_f32_e32 v223, v223, v209
	v_add_f32_e32 v222, v222, v206
	v_add_f32_e32 v223, v223, v210
	v_add_f32_e32 v222, v222, v211
	v_add_f32_e32 v223, v223, v216
	v_add_f32_e32 v222, v222, v213
	v_add_f32_e32 v223, v223, v217
	v_add_f32_e32 v222, v222, v214
	v_add_f32_e32 v223, v223, v218
	v_add_f32_e32 v222, v222, v215
	v_add_f32_e32 v223, v223, v219
	v_cvt_pk_bf16_f32 v232, v183, v184
	v_cvt_pk_bf16_f32 v233, v185, v186
	v_cvt_pk_bf16_f32 v234, v191, v192
	v_cvt_pk_bf16_f32 v235, v193, v194
	v_cvt_pk_bf16_f32 v236, v187, v188
	v_cvt_pk_bf16_f32 v237, v189, v190
	v_cvt_pk_bf16_f32 v238, v195, v196
	v_cvt_pk_bf16_f32 v239, v197, v199
	v_cvt_pk_bf16_f32 v228, v203, v204
	v_cvt_pk_bf16_f32 v229, v205, v206
	v_cvt_pk_bf16_f32 v230, v211, v213
	v_cvt_pk_bf16_f32 v231, v214, v215
	v_cvt_pk_bf16_f32 v240, v207, v208
	v_cvt_pk_bf16_f32 v241, v209, v210
	v_cvt_pk_bf16_f32 v242, v216, v217
	v_cvt_pk_bf16_f32 v243, v218, v219
	s_lshl_b32 s8, s29, 14
	s_add_i32 s29, s8, 0
	s_waitcnt lgkmcnt(7)
	v_mfma_f32_16x16x32_bf16 v[64:67], v[80:83], v[232:235], v[64:67]
	v_mfma_f32_16x16x32_bf16 v[68:71], v[80:83], v[236:239], v[68:71]
	s_waitcnt lgkmcnt(6)
	v_mfma_f32_16x16x32_bf16 v[72:75], v[84:87], v[232:235], v[72:75]
	v_mfma_f32_16x16x32_bf16 v[76:79], v[84:87], v[236:239], v[76:79]
	s_waitcnt lgkmcnt(5)
	v_mfma_f32_16x16x32_bf16 v[48:51], v[88:91], v[232:235], v[48:51]
	v_mfma_f32_16x16x32_bf16 v[52:55], v[88:91], v[236:239], v[52:55]
	s_waitcnt lgkmcnt(4)
	v_mfma_f32_16x16x32_bf16 v[56:59], v[92:95], v[232:235], v[56:59]
	v_mfma_f32_16x16x32_bf16 v[60:63], v[92:95], v[236:239], v[60:63]
	s_waitcnt lgkmcnt(3)
	v_mfma_f32_16x16x32_bf16 v[32:35], v[96:99], v[232:235], v[32:35]
	v_mfma_f32_16x16x32_bf16 v[36:39], v[96:99], v[236:239], v[36:39]
	s_waitcnt lgkmcnt(2)
	v_mfma_f32_16x16x32_bf16 v[40:43], v[100:103], v[232:235], v[40:43]
	v_mfma_f32_16x16x32_bf16 v[44:47], v[100:103], v[236:239], v[44:47]
	s_waitcnt lgkmcnt(1)
	v_mfma_f32_16x16x32_bf16 v[16:19], v[104:107], v[232:235], v[16:19]
	v_mfma_f32_16x16x32_bf16 v[20:23], v[104:107], v[236:239], v[20:23]
	s_waitcnt lgkmcnt(0)
	v_mfma_f32_16x16x32_bf16 v[24:27], v[108:111], v[232:235], v[24:27]
	v_mfma_f32_16x16x32_bf16 v[28:31], v[108:111], v[236:239], v[28:31]
	ds_read_b128 v[4:7], v250 offset:49152
	ds_read_b128 v[8:11], v250 offset:51200
	ds_read_b128 v[12:15], v250 offset:53248
	ds_read_b128 v[224:227], v250 offset:55296
	ds_read_b128 v[112:115], v250 offset:57344
	ds_read_b128 v[116:119], v250 offset:59392
	ds_read_b128 v[120:123], v250 offset:61440
	ds_read_b128 v[124:127], v250 offset:63488
	s_waitcnt lgkmcnt(7)
	v_mfma_f32_16x16x32_bf16 v[64:67], v[4:7], v[228:231], v[64:67]
	v_mfma_f32_16x16x32_bf16 v[68:71], v[4:7], v[240:243], v[68:71]
	s_waitcnt lgkmcnt(6)
	v_mfma_f32_16x16x32_bf16 v[72:75], v[8:11], v[228:231], v[72:75]
	v_mfma_f32_16x16x32_bf16 v[76:79], v[8:11], v[240:243], v[76:79]
	s_waitcnt lgkmcnt(5)
	v_mfma_f32_16x16x32_bf16 v[48:51], v[12:15], v[228:231], v[48:51]
	v_mfma_f32_16x16x32_bf16 v[52:55], v[12:15], v[240:243], v[52:55]
	s_waitcnt lgkmcnt(4)
	v_mfma_f32_16x16x32_bf16 v[56:59], v[224:227], v[228:231], v[56:59]
	v_mfma_f32_16x16x32_bf16 v[60:63], v[224:227], v[240:243], v[60:63]
	s_waitcnt lgkmcnt(3)
	v_mfma_f32_16x16x32_bf16 v[32:35], v[112:115], v[228:231], v[32:35]
	v_mfma_f32_16x16x32_bf16 v[36:39], v[112:115], v[240:243], v[36:39]
	s_waitcnt lgkmcnt(2)
	v_mfma_f32_16x16x32_bf16 v[40:43], v[116:119], v[228:231], v[40:43]
	v_mfma_f32_16x16x32_bf16 v[44:47], v[116:119], v[240:243], v[44:47]
	s_waitcnt lgkmcnt(1)
	v_mfma_f32_16x16x32_bf16 v[16:19], v[120:123], v[228:231], v[16:19]
	v_mfma_f32_16x16x32_bf16 v[20:23], v[120:123], v[240:243], v[20:23]
	s_waitcnt lgkmcnt(0)
	v_mfma_f32_16x16x32_bf16 v[24:27], v[124:127], v[228:231], v[24:27]
	v_mfma_f32_16x16x32_bf16 v[28:31], v[124:127], v[240:243], v[28:31]
	s_waitcnt vmcnt(0)
	s_barrier
; #define LAS __attribute__((address_space(3)))
; __device__ __forceinline__ void attn_unit(unsigned char* ws, const float* sub_g, LAS unsigned char* lds, int h, int qb, float negM, float lam) {
;     ...
;     float l = l0 + l1;
;     ...
;     asm volatile("s_waitcnt vmcnt(0) lgkmcnt(0)" ::: "memory");
;     __builtin_amdgcn_s_barrier();
;     l += __shfl_xor(l, 32);
;     const float inv = 1.0f / l;
;     LAS float* xw = (LAS float*)(lds + AT_XOFF + wq * 16384);
;     if (map == 1) {
;         const float f = inv * lam;
	v_mov_b32_e32 v251, v222
	v_mov_b32_e32 v252, v223
	s_nop 1
	v_permlane16_swap_b32_e32 v251, v222
	v_permlane16_swap_b32_e32 v252, v223
	v_add_f32_e32 v222, v222, v251
	v_add_f32_e32 v223, v223, v252
	v_mov_b32_e32 v251, v222
	v_mov_b32_e32 v252, v223
	s_nop 1
	v_permlane32_swap_b32_e32 v251, v222
	v_permlane32_swap_b32_e32 v252, v223
	v_add_f32_e32 v222, v222, v251
	v_add_f32_e32 v223, v223, v252
	v_and_b32_e32 v251, 16, v220
	v_cmp_ne_u32_e32 vcc, 0, v251
	v_cndmask_b32_e32 v88, v222, v223, vcc
	s_nop 7
	v_permlane16_swap_b32_e32 v64, v68
	v_permlane16_swap_b32_e32 v65, v69
	v_permlane16_swap_b32_e32 v66, v70
	v_permlane16_swap_b32_e32 v67, v71
	v_permlane16_swap_b32_e32 v72, v76
	v_permlane16_swap_b32_e32 v73, v77
	v_permlane16_swap_b32_e32 v74, v78
	v_permlane16_swap_b32_e32 v75, v79
	v_permlane16_swap_b32_e32 v48, v52
	v_permlane16_swap_b32_e32 v49, v53
	v_permlane16_swap_b32_e32 v50, v54
	v_permlane16_swap_b32_e32 v51, v55
	v_permlane16_swap_b32_e32 v56, v60
	v_permlane16_swap_b32_e32 v57, v61
	v_permlane16_swap_b32_e32 v58, v62
	v_permlane16_swap_b32_e32 v59, v63
	v_permlane16_swap_b32_e32 v32, v36
	v_permlane16_swap_b32_e32 v33, v37
	v_permlane16_swap_b32_e32 v34, v38
	v_permlane16_swap_b32_e32 v35, v39
	v_permlane16_swap_b32_e32 v40, v44
	v_permlane16_swap_b32_e32 v41, v45
	v_permlane16_swap_b32_e32 v42, v46
	v_permlane16_swap_b32_e32 v43, v47
	v_permlane16_swap_b32_e32 v16, v20
	v_permlane16_swap_b32_e32 v17, v21
	v_permlane16_swap_b32_e32 v18, v22
	v_permlane16_swap_b32_e32 v19, v23
	v_permlane16_swap_b32_e32 v24, v28
	v_permlane16_swap_b32_e32 v25, v29
	v_permlane16_swap_b32_e32 v26, v30
	v_permlane16_swap_b32_e32 v27, v31
	v_permlane32_swap_b32_e32 v64, v68
	v_permlane32_swap_b32_e32 v65, v69
	v_permlane32_swap_b32_e32 v66, v70
	v_permlane32_swap_b32_e32 v67, v71
	v_permlane32_swap_b32_e32 v72, v76
	v_permlane32_swap_b32_e32 v73, v77
	v_permlane32_swap_b32_e32 v74, v78
	v_permlane32_swap_b32_e32 v75, v79
	v_permlane32_swap_b32_e32 v48, v52
	v_permlane32_swap_b32_e32 v49, v53
	v_permlane32_swap_b32_e32 v50, v54
	v_permlane32_swap_b32_e32 v51, v55
	v_permlane32_swap_b32_e32 v56, v60
	v_permlane32_swap_b32_e32 v57, v61
	v_permlane32_swap_b32_e32 v58, v62
	v_permlane32_swap_b32_e32 v59, v63
	v_permlane32_swap_b32_e32 v32, v36
	v_permlane32_swap_b32_e32 v33, v37
	v_permlane32_swap_b32_e32 v34, v38
	v_permlane32_swap_b32_e32 v35, v39
	v_permlane32_swap_b32_e32 v40, v44
	v_permlane32_swap_b32_e32 v41, v45
	v_permlane32_swap_b32_e32 v42, v46
	v_permlane32_swap_b32_e32 v43, v47
	v_permlane32_swap_b32_e32 v16, v20
	v_permlane32_swap_b32_e32 v17, v21
	v_permlane32_swap_b32_e32 v18, v22
	v_permlane32_swap_b32_e32 v19, v23
	v_permlane32_swap_b32_e32 v24, v28
	v_permlane32_swap_b32_e32 v25, v29
	v_permlane32_swap_b32_e32 v26, v30
	v_permlane32_swap_b32_e32 v27, v31
	v_div_scale_f32 v89, s[30:31], v88, v88, 1.0
	v_rcp_f32_e32 v90, v89
	s_nop 1
	v_fma_f32 v80, -v89, v90, 1.0
	v_fmac_f32_e32 v90, v80, v90
	v_div_scale_f32 v80, vcc, 1.0, v88, 1.0
	v_mul_f32_e32 v81, v80, v90
	v_fma_f32 v82, -v89, v81, v80
	v_fmac_f32_e32 v81, v82, v90
	s_nop 1
	v_fma_f32 v80, -v89, v81, v80
	s_nop 1
	v_div_fmas_f32 v80, v80, v90, v81
	v_div_fixup_f32 v90, v80, v88, 1.0
	v_lshl_add_u32 v80, v221, 2, s29
	s_cmp_eq_u32 s28, 1
	s_cbranch_scc1 .Lepi_m1
